# GEMM phases: one static s_setprio 1 for waves 4-7 instead of per-phase toggles
# baseline (speedup 1.0000x reference)
.LBB0_342:
	v_readfirstlane_b32 s12, v188
	s_nop 3
	s_cmpk_lt_u32 s12, 0x100
	s_cbranch_scc1 .Lgemm_noprio
	s_setprio 1

.LBB0_583:
	s_setprio 0
	v_readlane_b32 s0, v246, 0
	v_readlane_b32 s1, v246, 1
	s_and_b64 vcc, exec, s[0:1]
	s_cbranch_vccz .LBB0_586
	s_cmp_lt_i32 s96, 7
	s_cbranch_scc1 .LBB0_588
	s_cmp_lg_u32 s96, 7
	s_cselect_b64 s[6:7], -1, 0
	s_cbranch_execz .LBB0_589
	s_branch .LBB0_590
